# grid barrier: non-leader WGs issue their agent-scope L1 invalidate at arrival (before polling) instead of after release (on v22)
# speedup vs baseline: 1.0080x; 1.0080x over previous
.LBB0_134:
	s_or_b64 exec, exec, s[14:15]
	v_cvt_f32_u32_e32 v4, v2
	s_waitcnt vmcnt(0)
	v_readfirstlane_b32 s3, v3
	v_sub_u32_e32 v3, 0, v2
	v_rcp_iflag_f32_e32 v4, v4
	v_add_u32_e32 v5, s3, v1
	v_mul_f32_e32 v4, 0x4f7ffffe, v4
	v_cvt_u32_f32_e32 v4, v4
	v_mul_lo_u32 v1, v3, v4
	v_mul_hi_u32 v1, v4, v1
	v_add_u32_e32 v1, v4, v1
	v_mul_hi_u32 v1, v5, v1
	v_mul_lo_u32 v3, v1, v2
	v_sub_u32_e32 v3, v5, v3
	v_add_u32_e32 v4, 1, v1
	v_cmp_ge_u32_e32 vcc, v3, v2
	s_nop 1
	v_cndmask_b32_e32 v1, v1, v4, vcc
	v_sub_u32_e32 v4, v3, v2
	v_cndmask_b32_e32 v3, v3, v4, vcc
	v_add_u32_e32 v4, 1, v1
	v_cmp_ge_u32_e32 vcc, v3, v2
	v_add_u32_e32 v3, 1, v5
	s_nop 0
	v_cndmask_b32_e32 v1, v1, v4, vcc
	v_mul_lo_u32 v4, v2, v1
	v_add_u32_e32 v2, v4, v2
	v_cmp_ne_u32_e32 vcc, v3, v2
	s_and_saveexec_b64 s[12:13], vcc
	s_xor_b64 s[12:13], exec, s[12:13]
	s_cbranch_execz .LBB0_148
	s_waitcnt lgkmcnt(0)
	buffer_inv sc1
	v_mov_b32_e32 v0, 0x2000
	global_load_dword v0, v0, s[10:11] offset:1024 sc1
	s_add_u32 s18, s10, 0x2400
	s_addc_u32 s19, s11, 0
	s_waitcnt vmcnt(0)
	v_cmp_eq_u32_e32 vcc, v0, v1
	s_and_saveexec_b64 s[14:15], vcc
	s_cbranch_execz .LBB0_147
	s_add_u32 s16, s8, 0xe000200
	s_addc_u32 s17, s9, 0
	s_mov_b32 s3, 1
	s_mov_b64 s[20:21], 0
	v_mov_b32_e32 v0, 0
	s_branch .LBB0_138

.LBB0_147:
	s_or_b64 exec, exec, s[14:15]
	s_waitcnt vmcnt(0)
	s_waitcnt vmcnt(0)

.LBB0_437:
	s_or_b64 exec, exec, s[16:17]
	v_cvt_f32_u32_e32 v4, v2
	s_waitcnt vmcnt(0)
	v_readfirstlane_b32 s14, v3
	v_sub_u32_e32 v3, 0, v2
	v_rcp_iflag_f32_e32 v4, v4
	v_add_u32_e32 v5, s14, v1
	v_mul_f32_e32 v4, 0x4f7ffffe, v4
	v_cvt_u32_f32_e32 v4, v4
	v_mul_lo_u32 v1, v3, v4
	v_mul_hi_u32 v1, v4, v1
	v_add_u32_e32 v1, v4, v1
	v_mul_hi_u32 v1, v5, v1
	v_mul_lo_u32 v3, v1, v2
	v_sub_u32_e32 v3, v5, v3
	v_add_u32_e32 v4, 1, v1
	v_cmp_ge_u32_e32 vcc, v3, v2
	s_nop 1
	v_cndmask_b32_e32 v1, v1, v4, vcc
	v_sub_u32_e32 v4, v3, v2
	v_cndmask_b32_e32 v3, v3, v4, vcc
	v_add_u32_e32 v4, 1, v1
	v_cmp_ge_u32_e32 vcc, v3, v2
	v_add_u32_e32 v3, 1, v5
	s_nop 0
	v_cndmask_b32_e32 v1, v1, v4, vcc
	v_mul_lo_u32 v4, v2, v1
	v_add_u32_e32 v2, v4, v2
	v_cmp_ne_u32_e32 vcc, v3, v2
	s_and_saveexec_b64 s[14:15], vcc
	s_xor_b64 s[14:15], exec, s[14:15]
	s_cbranch_execz .LBB0_451
	s_waitcnt lgkmcnt(0)
	buffer_inv sc1
	v_mov_b32_e32 v0, 0x2000
	global_load_dword v0, v0, s[12:13] offset:1024 sc1
	s_add_u32 s22, s12, 0x2400
	s_addc_u32 s23, s13, 0
	s_waitcnt vmcnt(0)
	v_cmp_eq_u32_e32 vcc, v0, v1
	s_and_saveexec_b64 s[16:17], vcc
	s_cbranch_execz .LBB0_450
	s_add_u32 s18, s10, 0xe000200
	s_addc_u32 s19, s11, 0
	s_mov_b32 s26, 1
	s_mov_b64 s[34:35], 0
	v_mov_b32_e32 v0, 0
	s_branch .LBB0_441

.LBB0_450:
	s_or_b64 exec, exec, s[16:17]
	s_waitcnt vmcnt(0)
	s_waitcnt vmcnt(0)

.LBB0_592:
	s_or_b64 exec, exec, s[16:17]
	v_cvt_f32_u32_e32 v4, v2
	s_waitcnt vmcnt(0)
	v_readfirstlane_b32 s14, v3
	v_sub_u32_e32 v3, 0, v2
	v_rcp_iflag_f32_e32 v4, v4
	v_add_u32_e32 v5, s14, v1
	v_mul_f32_e32 v4, 0x4f7ffffe, v4
	v_cvt_u32_f32_e32 v4, v4
	v_mul_lo_u32 v1, v3, v4
	v_mul_hi_u32 v1, v4, v1
	v_add_u32_e32 v1, v4, v1
	v_mul_hi_u32 v1, v5, v1
	v_mul_lo_u32 v3, v1, v2
	v_sub_u32_e32 v3, v5, v3
	v_add_u32_e32 v4, 1, v1
	v_cmp_ge_u32_e32 vcc, v3, v2
	s_nop 1
	v_cndmask_b32_e32 v1, v1, v4, vcc
	v_sub_u32_e32 v4, v3, v2
	v_cndmask_b32_e32 v3, v3, v4, vcc
	v_add_u32_e32 v4, 1, v1
	v_cmp_ge_u32_e32 vcc, v3, v2
	v_add_u32_e32 v3, 1, v5
	s_nop 0
	v_cndmask_b32_e32 v1, v1, v4, vcc
	v_mul_lo_u32 v4, v2, v1
	v_add_u32_e32 v2, v4, v2
	v_cmp_ne_u32_e32 vcc, v3, v2
	s_and_saveexec_b64 s[14:15], vcc
	s_xor_b64 s[14:15], exec, s[14:15]
	s_cbranch_execz .LBB0_606
	s_waitcnt lgkmcnt(0)
	buffer_inv sc1
	v_mov_b32_e32 v0, 0x2000
	global_load_dword v0, v0, s[12:13] offset:1024 sc1
	s_add_u32 s34, s12, 0x2400
	s_addc_u32 s35, s13, 0
	s_waitcnt vmcnt(0)
	v_cmp_eq_u32_e32 vcc, v0, v1
	s_and_saveexec_b64 s[16:17], vcc
	s_cbranch_execz .LBB0_605
	s_add_u32 s18, s10, 0xe000200
	s_addc_u32 s19, s11, 0
	s_mov_b32 s26, 1
	s_mov_b64 s[36:37], 0
	v_mov_b32_e32 v0, 0
	s_branch .LBB0_596

.LBB0_1006:
	s_or_b64 exec, exec, s[18:19]
	v_cvt_f32_u32_e32 v4, v2
	s_waitcnt vmcnt(0)
	v_readfirstlane_b32 s16, v3
	v_sub_u32_e32 v3, 0, v2
	v_rcp_iflag_f32_e32 v4, v4
	v_add_u32_e32 v5, s16, v1
	v_mul_f32_e32 v4, 0x4f7ffffe, v4
	v_cvt_u32_f32_e32 v4, v4
	v_mul_lo_u32 v1, v3, v4
	v_mul_hi_u32 v1, v4, v1
	v_add_u32_e32 v1, v4, v1
	v_mul_hi_u32 v1, v5, v1
	v_mul_lo_u32 v3, v1, v2
	v_sub_u32_e32 v3, v5, v3
	v_add_u32_e32 v4, 1, v1
	v_cmp_ge_u32_e32 vcc, v3, v2
	s_nop 1
	v_cndmask_b32_e32 v1, v1, v4, vcc
	v_sub_u32_e32 v4, v3, v2
	v_cndmask_b32_e32 v3, v3, v4, vcc
	v_add_u32_e32 v4, 1, v1
	v_cmp_ge_u32_e32 vcc, v3, v2
	v_add_u32_e32 v3, 1, v5
	s_nop 0
	v_cndmask_b32_e32 v1, v1, v4, vcc
	v_mul_lo_u32 v4, v2, v1
	v_add_u32_e32 v2, v4, v2
	v_cmp_ne_u32_e32 vcc, v3, v2
	s_and_saveexec_b64 s[16:17], vcc
	s_xor_b64 s[16:17], exec, s[16:17]
	s_cbranch_execz .LBB0_1020
	s_waitcnt lgkmcnt(0)
	buffer_inv sc1
	v_mov_b32_e32 v0, 0x2000
	global_load_dword v0, v0, s[14:15] offset:1024 sc1
	s_add_u32 s38, s14, 0x2400
	s_addc_u32 s39, s15, 0
	s_waitcnt vmcnt(0)
	v_cmp_eq_u32_e32 vcc, v0, v1
	s_and_saveexec_b64 s[18:19], vcc
	s_cbranch_execz .LBB0_1019
	s_add_u32 s36, s12, 0xe000200
	s_addc_u32 s37, s13, 0
	s_mov_b32 s26, 1
	s_mov_b64 s[40:41], 0
	v_mov_b32_e32 v0, 0
	s_branch .LBB0_1010

.LBB0_1019:
	s_or_b64 exec, exec, s[18:19]
	s_waitcnt vmcnt(0)
	s_waitcnt vmcnt(0)

.LBB0_1307:
	s_or_b64 exec, exec, s[18:19]
	v_cvt_f32_u32_e32 v4, v2
	s_waitcnt vmcnt(0)
	v_readfirstlane_b32 s16, v3
	v_sub_u32_e32 v3, 0, v2
	v_rcp_iflag_f32_e32 v4, v4
	v_add_u32_e32 v5, s16, v1
	v_mul_f32_e32 v4, 0x4f7ffffe, v4
	v_cvt_u32_f32_e32 v4, v4
	v_mul_lo_u32 v1, v3, v4
	v_mul_hi_u32 v1, v4, v1
	v_add_u32_e32 v1, v4, v1
	v_mul_hi_u32 v1, v5, v1
	v_mul_lo_u32 v3, v1, v2
	v_sub_u32_e32 v3, v5, v3
	v_add_u32_e32 v4, 1, v1
	v_cmp_ge_u32_e32 vcc, v3, v2
	s_nop 1
	v_cndmask_b32_e32 v1, v1, v4, vcc
	v_sub_u32_e32 v4, v3, v2
	v_cndmask_b32_e32 v3, v3, v4, vcc
	v_add_u32_e32 v4, 1, v1
	v_cmp_ge_u32_e32 vcc, v3, v2
	v_add_u32_e32 v3, 1, v5
	s_nop 0
	v_cndmask_b32_e32 v1, v1, v4, vcc
	v_mul_lo_u32 v4, v2, v1
	v_add_u32_e32 v2, v4, v2
	v_cmp_ne_u32_e32 vcc, v3, v2
	s_and_saveexec_b64 s[16:17], vcc
	s_xor_b64 s[16:17], exec, s[16:17]
	s_cbranch_execz .LBB0_1321
	s_waitcnt lgkmcnt(0)
	buffer_inv sc1
	v_mov_b32_e32 v0, 0x2000
	global_load_dword v0, v0, s[14:15] offset:1024 sc1
	s_add_u32 s36, s14, 0x2400
	s_addc_u32 s37, s15, 0
	s_waitcnt vmcnt(0)
	v_cmp_eq_u32_e32 vcc, v0, v1
	s_and_saveexec_b64 s[18:19], vcc
	s_cbranch_execz .LBB0_1320
	s_add_u32 s20, s12, 0xe000200
	s_addc_u32 s21, s13, 0
	s_mov_b32 s26, 1
	s_mov_b64 s[38:39], 0
	v_mov_b32_e32 v0, 0
	s_branch .LBB0_1311

.LBB0_1462:
	s_or_b64 exec, exec, s[18:19]
	v_cvt_f32_u32_e32 v4, v2
	s_waitcnt vmcnt(0)
	v_readfirstlane_b32 s16, v3
	v_sub_u32_e32 v3, 0, v2
	v_rcp_iflag_f32_e32 v4, v4
	v_add_u32_e32 v5, s16, v1
	v_mul_f32_e32 v4, 0x4f7ffffe, v4
	v_cvt_u32_f32_e32 v4, v4
	v_mul_lo_u32 v1, v3, v4
	v_mul_hi_u32 v1, v4, v1
	v_add_u32_e32 v1, v4, v1
	v_mul_hi_u32 v1, v5, v1
	v_mul_lo_u32 v3, v1, v2
	v_sub_u32_e32 v3, v5, v3
	v_add_u32_e32 v4, 1, v1
	v_cmp_ge_u32_e32 vcc, v3, v2
	s_nop 1
	v_cndmask_b32_e32 v1, v1, v4, vcc
	v_sub_u32_e32 v4, v3, v2
	v_cndmask_b32_e32 v3, v3, v4, vcc
	v_add_u32_e32 v4, 1, v1
	v_cmp_ge_u32_e32 vcc, v3, v2
	v_add_u32_e32 v3, 1, v5
	s_nop 0
	v_cndmask_b32_e32 v1, v1, v4, vcc
	v_mul_lo_u32 v4, v2, v1
	v_add_u32_e32 v2, v4, v2
	v_cmp_ne_u32_e32 vcc, v3, v2
	s_and_saveexec_b64 s[16:17], vcc
	s_xor_b64 s[16:17], exec, s[16:17]
	s_cbranch_execz .LBB0_1476
	s_waitcnt lgkmcnt(0)
	buffer_inv sc1
	v_mov_b32_e32 v0, 0x2000
	global_load_dword v0, v0, s[14:15] offset:1024 sc1
	s_add_u32 s22, s14, 0x2400
	s_addc_u32 s23, s15, 0
	s_waitcnt vmcnt(0)
	v_cmp_eq_u32_e32 vcc, v0, v1
	s_and_saveexec_b64 s[18:19], vcc
	s_cbranch_execz .LBB0_1475
	s_add_u32 s20, s12, 0xe000200
	s_addc_u32 s21, s13, 0
	s_mov_b32 s26, 1
	s_mov_b64 s[36:37], 0
	v_mov_b32_e32 v0, 0
	s_branch .LBB0_1466

.LBB0_1780:
	s_or_b64 exec, exec, s[16:17]
	v_cvt_f32_u32_e32 v4, v2
	s_waitcnt vmcnt(0)
	v_readfirstlane_b32 s14, v3
	v_sub_u32_e32 v3, 0, v2
	v_rcp_iflag_f32_e32 v4, v4
	v_add_u32_e32 v5, s14, v1
	v_mul_f32_e32 v4, 0x4f7ffffe, v4
	v_cvt_u32_f32_e32 v4, v4
	v_mul_lo_u32 v1, v3, v4
	v_mul_hi_u32 v1, v4, v1
	v_add_u32_e32 v1, v4, v1
	v_mul_hi_u32 v1, v5, v1
	v_mul_lo_u32 v3, v1, v2
	v_sub_u32_e32 v3, v5, v3
	v_add_u32_e32 v4, 1, v1
	v_cmp_ge_u32_e32 vcc, v3, v2
	s_nop 1
	v_cndmask_b32_e32 v1, v1, v4, vcc
	v_sub_u32_e32 v4, v3, v2
	v_cndmask_b32_e32 v3, v3, v4, vcc
	v_add_u32_e32 v4, 1, v1
	v_cmp_ge_u32_e32 vcc, v3, v2
	v_add_u32_e32 v3, 1, v5
	s_nop 0
	v_cndmask_b32_e32 v1, v1, v4, vcc
	v_mul_lo_u32 v4, v2, v1
	v_add_u32_e32 v2, v4, v2
	v_cmp_ne_u32_e32 vcc, v3, v2
	s_and_saveexec_b64 s[14:15], vcc
	s_xor_b64 s[14:15], exec, s[14:15]
	s_cbranch_execz .LBB0_1794
	s_waitcnt lgkmcnt(0)
	buffer_inv sc1
	v_mov_b32_e32 v0, 0x2000
	global_load_dword v0, v0, s[12:13] offset:1024 sc1
	s_add_u32 s20, s12, 0x2400
	s_addc_u32 s21, s13, 0
	s_waitcnt vmcnt(0)
	v_cmp_eq_u32_e32 vcc, v0, v1
	s_and_saveexec_b64 s[16:17], vcc
	s_cbranch_execz .LBB0_1793
	s_add_u32 s18, s10, 0xe000200
	s_addc_u32 s19, s11, 0
	s_mov_b32 s26, 1
	s_mov_b64 s[22:23], 0
	v_mov_b32_e32 v0, 0
	s_branch .LBB0_1784

.LBB0_1876:
	s_or_b64 exec, exec, s[20:21]
	v_cvt_f32_u32_e32 v4, v2
	s_waitcnt vmcnt(0)
	v_readfirstlane_b32 s18, v3
	v_sub_u32_e32 v3, 0, v2
	v_rcp_iflag_f32_e32 v4, v4
	v_add_u32_e32 v5, s18, v1
	v_mul_f32_e32 v4, 0x4f7ffffe, v4
	v_cvt_u32_f32_e32 v4, v4
	v_mul_lo_u32 v1, v3, v4
	v_mul_hi_u32 v1, v4, v1
	v_add_u32_e32 v1, v4, v1
	v_mul_hi_u32 v1, v5, v1
	v_mul_lo_u32 v3, v1, v2
	v_sub_u32_e32 v3, v5, v3
	v_add_u32_e32 v4, 1, v1
	v_cmp_ge_u32_e32 vcc, v3, v2
	s_nop 1
	v_cndmask_b32_e32 v1, v1, v4, vcc
	v_sub_u32_e32 v4, v3, v2
	v_cndmask_b32_e32 v3, v3, v4, vcc
	v_add_u32_e32 v4, 1, v1
	v_cmp_ge_u32_e32 vcc, v3, v2
	v_add_u32_e32 v3, 1, v5
	s_nop 0
	v_cndmask_b32_e32 v1, v1, v4, vcc
	v_mul_lo_u32 v4, v2, v1
	v_add_u32_e32 v2, v4, v2
	v_cmp_ne_u32_e32 vcc, v3, v2
	s_and_saveexec_b64 s[18:19], vcc
	s_xor_b64 s[18:19], exec, s[18:19]
	s_cbranch_execz .LBB0_1890
	s_waitcnt lgkmcnt(0)
	buffer_inv sc1
	v_mov_b32_e32 v0, 0x2000
	global_load_dword v0, v0, s[10:11] offset:1024 sc1
	s_add_u32 s34, s10, 0x2400
	s_addc_u32 s35, s11, 0
	s_waitcnt vmcnt(0)
	v_cmp_eq_u32_e32 vcc, v0, v1
	s_and_saveexec_b64 s[20:21], vcc
	s_cbranch_execz .LBB0_1889
	s_add_u32 s22, s4, 0xe000200
	s_addc_u32 s23, s5, 0
	s_mov_b32 s25, 1
	s_mov_b64 s[36:37], 0
	v_mov_b32_e32 v0, 0
	s_branch .LBB0_1880

.LBB0_1889:
	s_or_b64 exec, exec, s[20:21]
	s_waitcnt vmcnt(0)
	s_waitcnt vmcnt(0)
